# strategy 7 (instruction selection): DPP row reductions replace four of the six ds_bpermute butterfly steps in the P0 and P10 RMS row loops (on top of v41)
# baseline (speedup 1.0000x reference)
; __device__ __forceinline__ unsigned pk(float lo, float hi) { f32x2_t v = {lo, hi}; bf16x2_t b = __builtin_convertvector(v, bf16x2_t); return __builtin_bit_cast(unsigned, b); }
; __device__ __forceinline__ float wave_sum(float v) {
; #pragma unroll
;     for (int o = 1; o < 64; o <<= 1) v += __shfl_xor(v, o);
;     return v;
; }
; __device__ __forceinline__ void rms_row_bf16(const float* xrow, bf16_t* orow, int lane) {
;     const f32x4* xr = (const f32x4*)xrow + lane; f32x4 v[4]; float s = 0.f;
; #pragma unroll
;     for (int j = 0; j < 4; ++j) { v[j] = xr[64 * j]; s += (v[j].x * v[j].x + v[j].y * v[j].y) + (v[j].z * v[j].z + v[j].w * v[j].w); }
;     const float rstd = rsqrtf(wave_sum(s) * (1.0f / DM) + EPSN);
;     u32x2* o8 = (u32x2*)orow + lane;
; #pragma unroll
;     for (int j = 0; j < 4; ++j) { u32x2 w; w.x = pk(v[j].x * rstd, v[j].y * rstd); w.y = pk(v[j].z * rstd, v[j].w * rstd); o8[64 * j] = w; }
; }
.LBB0_261:
	v_lshl_add_u64 v[24:25], v[2:3], 4, s[12:13]
	global_load_dwordx4 v[8:11], v[24:25], off
	global_load_dwordx4 v[12:15], v[24:25], off offset:1024
	global_load_dwordx4 v[16:19], v[24:25], off offset:3072
	global_load_dwordx4 v[20:23], v[24:25], off offset:2048
	s_lshl_b64 s[10:11], s[10:11], 11
	s_add_u32 s8, s8, 0x800
	s_addc_u32 s9, s9, 0
	s_add_u32 s6, s6, 0x800000
	s_addc_u32 s7, s7, 0
	s_cmp_eq_u32 s6, 0xc000000
	s_waitcnt vmcnt(3)
	v_pk_mul_f32 v[24:25], v[10:11], v[10:11]
	v_pk_mul_f32 v[26:27], v[8:9], v[8:9]
	s_waitcnt vmcnt(2)
	v_pk_mul_f32 v[28:29], v[14:15], v[14:15]
	v_pk_mul_f32 v[30:31], v[12:13], v[12:13]
	v_pk_mov_b32 v[36:37], v[26:27], v[24:25] op_sel:[1,0]
	v_mov_b32_e32 v27, v25
	v_pk_mov_b32 v[24:25], v[30:31], v[28:29] op_sel:[1,0]
	v_mov_b32_e32 v31, v29
	s_waitcnt vmcnt(1)
	v_mul_f32_e32 v35, v17, v17
	s_waitcnt vmcnt(0)
	v_mul_f32_e32 v32, v21, v21
	v_mul_f32_e32 v34, v23, v23
	v_pk_add_f32 v[26:27], v[36:37], v[26:27]
	v_pk_add_f32 v[24:25], v[24:25], v[30:31]
	v_mul_f32_e32 v7, v16, v16
	v_mul_f32_e32 v38, v18, v18
	v_mul_f32_e32 v39, v19, v19
	v_pk_fma_f32 v[28:29], v[20:21], v[20:21], v[32:33] op_sel_hi:[1,1,0]
	v_pk_fma_f32 v[32:33], v[22:23], v[22:23], v[34:35] op_sel_hi:[1,1,0]
	v_pk_add_f32 v[26:27], v[26:27], v[26:27] op_sel:[0,1] op_sel_hi:[1,0]
	v_pk_add_f32 v[24:25], v[24:25], v[24:25] op_sel:[0,1] op_sel_hi:[1,0]
	v_mov_b32_e32 v29, v38
	v_mov_b32_e32 v33, v39
	v_mov_b32_e32 v27, v7
	v_mov_b32_e32 v25, v35
	v_pk_add_f32 v[28:29], v[28:29], v[32:33]
	v_pk_add_f32 v[24:25], v[26:27], v[24:25]
	s_nop 0
	v_pk_add_f32 v[24:25], v[24:25], v[28:29]
	s_nop 0
	v_add_f32_e32 v7, v24, v25
	s_nop 1
	v_add_f32_dpp v7, v7, v7 quad_perm:[1,0,3,2] row_mask:0xf bank_mask:0xf
	s_nop 1
	v_add_f32_dpp v7, v7, v7 quad_perm:[2,3,0,1] row_mask:0xf bank_mask:0xf
	s_nop 1
	v_add_f32_dpp v7, v7, v7 row_half_mirror row_mask:0xf bank_mask:0xf
	s_nop 1
	v_add_f32_dpp v7, v7, v7 row_mirror row_mask:0xf bank_mask:0xf
	ds_bpermute_b32 v24, v216, v7
	s_waitcnt lgkmcnt(0)
	v_add_f32_e32 v7, v7, v24
	ds_bpermute_b32 v26, v217, v7
	v_lshl_add_u64 v[24:25], v[4:5], 0, s[10:11]
	s_waitcnt lgkmcnt(0)
	v_add_f32_e32 v7, v7, v26
	v_fmamk_f32 v7, v7, 0x3a800000, v6
	v_mul_f32_e32 v26, 0x4b800000, v7
	v_cmp_gt_f32_e32 vcc, s3, v7
	s_nop 1
	v_cndmask_b32_e32 v7, v7, v26, vcc
	v_rsq_f32_e32 v7, v7
	s_nop 0
	v_mul_f32_e32 v26, 0x45800000, v7
	v_cndmask_b32_e32 v26, v7, v26, vcc
	v_pk_mul_f32 v[8:9], v[8:9], v[26:27] op_sel_hi:[1,0]
	v_pk_mul_f32 v[10:11], v[10:11], v[26:27] op_sel_hi:[1,0]
	v_pk_mul_f32 v[12:13], v[12:13], v[26:27] op_sel_hi:[1,0]
	v_pk_mul_f32 v[14:15], v[14:15], v[26:27] op_sel_hi:[1,0]
	v_pk_mul_f32 v[20:21], v[20:21], v[26:27] op_sel_hi:[1,0]
	v_pk_mul_f32 v[22:23], v[22:23], v[26:27] op_sel_hi:[1,0]
	v_pk_mul_f32 v[16:17], v[16:17], v[26:27] op_sel_hi:[1,0]
	v_pk_mul_f32 v[18:19], v[18:19], v[26:27] op_sel_hi:[1,0]
	v_cvt_pk_bf16_f32 v8, v8, v9
	v_cvt_pk_bf16_f32 v9, v10, v11
	v_cvt_pk_bf16_f32 v10, v12, v13
	v_cvt_pk_bf16_f32 v11, v14, v15
	v_cvt_pk_bf16_f32 v12, v20, v21
	v_cvt_pk_bf16_f32 v13, v22, v23
	v_cvt_pk_bf16_f32 v14, v16, v17
	v_cvt_pk_bf16_f32 v15, v18, v19
	global_store_dwordx2 v[24:25], v[8:9], off
	global_store_dwordx2 v[24:25], v[10:11], off offset:512
	global_store_dwordx2 v[24:25], v[12:13], off offset:1024
	global_store_dwordx2 v[24:25], v[14:15], off offset:1536
	s_cbranch_scc1 .LBB0_266

; __device__ __forceinline__ float bflo(unsigned w) { return __uint_as_float(w << 16); }
; __device__ __forceinline__ float bfhi(unsigned w) { return __uint_as_float(w & 0xffff0000u); }
; __device__ __forceinline__ unsigned pk(float lo, float hi) { f32x2_t v = {lo, hi}; bf16x2_t b = __builtin_convertvector(v, bf16x2_t); return __builtin_bit_cast(unsigned, b); }
; __global__ void __launch_bounds__(512) fwd_megakernel(Args a) {
;     ...
;             _Pragma("nounroll") for (int rt_ = 0; rt_ < REP_THIN; ++rt_) if (PH(10)) for (int m = gw, it_ = 0; it_ < T / 2048; ++it_, m += 2048) {
;                 const bf16_t* row = CDOWN + (size_t)m * 768;
;                 const unsigned* pq = (const unsigned*)row + 3 * lane; const unsigned* pkv = (const unsigned*)(row + 384) + 2 * lane;
;                 const unsigned q0 = pq[0], q1 = pq[1], q2 = pq[2], k0 = pkv[0], k1 = pkv[1];
;                 float sq_ = bflo(q0) * bflo(q0) + bfhi(q0) * bfhi(q0) + bflo(q1) * bflo(q1) + bfhi(q1) * bfhi(q1) + bflo(q2) * bflo(q2) + bfhi(q2) * bfhi(q2);
;                 float sk_ = bflo(k0) * bflo(k0) + bfhi(k0) * bfhi(k0) + bflo(k1) * bflo(k1) + bfhi(k1) * bfhi(k1);
;                 const float rq = rsqrtf(wave_sum(sq_) * (1.0f / 384.0f) + EPSN), rk = rsqrtf(wave_sum(sk_) * (1.0f / 256.0f) + EPSN);
;                 unsigned* oq = (unsigned*)(CQN + (size_t)m * 384) + 3 * lane; unsigned* ok = (unsigned*)(CKVN + (size_t)m * 256) + 2 * lane;
;                 oq[0] = pk(bflo(q0) * rq, bfhi(q0) * rq); oq[1] = pk(bflo(q1) * rq, bfhi(q1) * rq); oq[2] = pk(bflo(q2) * rq, bfhi(q2) * rq);
;                 ok[0] = pk(bflo(k0) * rk, bfhi(k0) * rk); ok[1] = pk(bflo(k1) * rk, bfhi(k1) * rk);
;                 if (lane < 16) { const float x1 = __uint_as_float((unsigned)row[640 + lane] << 16), x2 = __uint_as_float((unsigned)row[656 + lane] << 16);
;                     float c, s; rope_cs(m & (SEQ - 1), INVF_TAB[lane], c, s);
;                     const unsigned w = pk(x1 * c - x2 * s, x2 * c + x1 * s);
;                     KROPE[(size_t)m * 32 + lane] = (bf16_t)(w & 0xffffu); KROPE[(size_t)m * 32 + 16 + lane] = (bf16_t)(w >> 16); }
.LBB0_722:
	v_lshl_add_u64 v[12:13], s[16:17], 0, v[6:7]
	v_lshl_add_u64 v[16:17], v[8:9], 0, v[6:7]
	global_load_dwordx3 v[12:14], v[12:13], off offset:-8
	v_add_co_u32_e32 v16, vcc, 0x12300000, v16
	s_mov_b32 s8, 0x3b800000
	s_nop 0
	v_addc_co_u32_e32 v17, vcc, 0, v17, vcc
	global_load_dwordx2 v[18:19], v[16:17], off offset:768
	s_mov_b32 s9, 0x3b2aaaab
	s_mov_b32 s11, 0x3201000
	s_waitcnt vmcnt(1)
	v_and_b32_e32 v21, 0xffff0000, v12
	v_lshlrev_b32_e32 v20, 16, v12
	v_mul_f32_e32 v26, v21, v21
	v_lshlrev_b32_e32 v22, 16, v13
	v_and_b32_e32 v23, 0xffff0000, v13
	v_pk_fma_f32 v[26:27], v[20:21], v[20:21], v[26:27] op_sel_hi:[1,1,0]
	s_waitcnt vmcnt(0)
	v_lshlrev_b32_e32 v16, 16, v18
	v_and_b32_e32 v17, 0xffff0000, v18
	v_lshlrev_b32_e32 v24, 16, v14
	v_and_b32_e32 v25, 0xffff0000, v14
	v_lshlrev_b32_e32 v14, 16, v19
	v_and_b32_e32 v15, 0xffff0000, v19
	v_pk_mul_f32 v[28:29], v[22:23], v[22:23]
	v_pk_fma_f32 v[26:27], v[22:23], v[22:23], v[26:27]
	v_pk_mul_f32 v[32:33], v[16:17], v[16:17]
	v_pk_mul_f32 v[30:31], v[24:25], v[24:25]
	v_pk_mul_f32 v[34:35], v[14:15], v[14:15]
	v_mov_b32_e32 v28, v32
	v_pk_mov_b32 v[26:27], v[32:33], v[26:27] op_sel:[1,0]
	v_lshl_add_u64 v[18:19], s[12:13], 0, v[6:7]
	v_pk_add_f32 v[26:27], v[28:29], v[26:27]
	v_mov_b32_e32 v28, v34
	v_mov_b32_e32 v29, v30
	v_pk_add_f32 v[26:27], v[26:27], v[28:29]
	v_mov_b32_e32 v30, v35
	v_pk_add_f32 v[26:27], v[30:31], v[26:27]
	v_lshl_add_u64 v[12:13], s[14:15], 0, v[4:5]
	s_nop 0
	v_add_f32_dpp v26, v26, v26 quad_perm:[1,0,3,2] row_mask:0xf bank_mask:0xf
	v_add_f32_dpp v27, v27, v27 quad_perm:[1,0,3,2] row_mask:0xf bank_mask:0xf
	s_nop 0
	v_add_f32_dpp v26, v26, v26 quad_perm:[2,3,0,1] row_mask:0xf bank_mask:0xf
	v_add_f32_dpp v27, v27, v27 quad_perm:[2,3,0,1] row_mask:0xf bank_mask:0xf
	s_nop 0
	v_add_f32_dpp v26, v26, v26 row_half_mirror row_mask:0xf bank_mask:0xf
	v_add_f32_dpp v27, v27, v27 row_half_mirror row_mask:0xf bank_mask:0xf
	s_nop 0
	v_add_f32_dpp v26, v26, v26 row_mirror row_mask:0xf bank_mask:0xf
	v_add_f32_dpp v27, v27, v27 row_mirror row_mask:0xf bank_mask:0xf
	ds_bpermute_b32 v29, v216, v27
	ds_bpermute_b32 v28, v216, v26
	s_waitcnt lgkmcnt(0)
	v_pk_add_f32 v[26:27], v[26:27], v[28:29]
	ds_bpermute_b32 v29, v217, v27
	ds_bpermute_b32 v28, v217, v26
	s_waitcnt lgkmcnt(0)
	v_pk_add_f32 v[26:27], v[26:27], v[28:29]
	s_nop 0
	v_pk_fma_f32 v[26:27], v[26:27], s[8:9], v[192:193] op_sel_hi:[1,1,0]
	s_nop 0
	v_mul_f32_e32 v28, 0x4b800000, v27
	v_cmp_gt_f32_e32 vcc, s37, v27
	v_cmp_gt_f32_e64 s[8:9], s37, v26
	s_nop 0
	v_cndmask_b32_e32 v27, v27, v28, vcc
	v_rsq_f32_e32 v27, v27
	s_nop 0
	v_mul_f32_e32 v28, 0x45800000, v27
	v_cndmask_b32_e32 v28, v27, v28, vcc
	v_pk_mul_f32 v[20:21], v[28:29], v[20:21] op_sel_hi:[0,1]
	v_pk_mul_f32 v[22:23], v[28:29], v[22:23] op_sel_hi:[0,1]
	v_cvt_pk_bf16_f32 v20, v20, v21
	v_cvt_pk_bf16_f32 v21, v22, v23
	v_pk_mul_f32 v[22:23], v[28:29], v[24:25] op_sel_hi:[0,1]
	v_add_co_u32_e32 v18, vcc, s11, v18
	v_cvt_pk_bf16_f32 v22, v22, v23
	s_nop 0
	v_addc_co_u32_e32 v19, vcc, 0, v19, vcc
	global_store_dwordx3 v[18:19], v[20:22], off
	v_mul_f32_e32 v18, 0x4b800000, v26
	v_cndmask_b32_e64 v18, v26, v18, s[8:9]
	v_rsq_f32_e32 v18, v18
	v_add_co_u32_e32 v12, vcc, 0x5a01000, v12
	v_mul_f32_e32 v19, 0x45800000, v18
	v_cndmask_b32_e64 v18, v18, v19, s[8:9]
	v_pk_mul_f32 v[16:17], v[18:19], v[16:17] op_sel_hi:[0,1]
	v_pk_mul_f32 v[14:15], v[18:19], v[14:15] op_sel_hi:[0,1]
	v_cvt_pk_bf16_f32 v16, v16, v17
	v_cvt_pk_bf16_f32 v17, v14, v15
	v_addc_co_u32_e32 v13, vcc, 0, v13, vcc
	global_store_dwordx2 v[12:13], v[16:17], off
	s_and_saveexec_b64 s[8:9], s[6:7]
	s_cbranch_execz .LBB0_721
	global_load_dword v14, v[0:1], off
	s_add_i32 s11, s54, s10
	s_and_b32 s11, s11, 0x3fff
	v_cvt_f32_u32_e32 v15, s11
	v_lshl_add_u64 v[12:13], v[10:11], 0, v[6:7]
	v_add_co_u32_e32 v12, vcc, 0x12300000, v12
	s_waitcnt vmcnt(0)
	v_mul_f32_e32 v14, v14, v15
	v_mul_f32_e32 v15, 0.15915494, v14
	v_rndne_f32_e32 v15, v15
	v_fmac_f32_e32 v14, 0xc0c90fdb, v15
	v_fmac_f32_e32 v14, 0x343bbd2e, v15
	v_mul_f32_e32 v15, 0.15915494, v14
	v_addc_co_u32_e32 v13, vcc, 0, v13, vcc
	v_sin_f32_e32 v14, v15
	v_cos_f32_e32 v16, v15
	global_load_ushort v15, v[12:13], off offset:1280
	s_nop 0
	global_load_ushort v12, v[12:13], off offset:1312
	s_waitcnt vmcnt(0)
	v_lshlrev_b32_e32 v13, 16, v12
	v_lshlrev_b32_e32 v12, 16, v15
	v_pk_mul_f32 v[14:15], v[14:15], v[12:13] op_sel:[0,1] op_sel_hi:[0,0]
	v_pk_fma_f32 v[18:19], v[16:17], v[12:13], v[14:15] neg_lo:[0,0,1] neg_hi:[0,0,1]
	v_pk_fma_f32 v[12:13], v[16:17], v[12:13], v[14:15] op_sel_hi:[0,1,1]
	v_cvt_pk_bf16_f32 v14, v18, v13
	v_lshl_add_u64 v[12:13], s[14:15], 0, v[2:3]
	v_add_co_u32_e32 v12, vcc, 0x2e00000, v12
	s_nop 1
	v_addc_co_u32_e32 v13, vcc, 0, v13, vcc
	global_store_short v[12:13], v14, off
	global_store_short_d16_hi v[12:13], v14, off offset:32
	s_branch .LBB0_721
